# NSA selected-branch: block-list lookups via v_readlane from a per-lane copy instead of 3 LDS round trips per 64-key block
# speedup vs baseline: 1.1035x; 1.0047x over previous
; DI int my_tid() { int t = threadIdx.x; asm volatile("" : "+v"(t)); return t; }
; template <int MODE>
; DI void nsa_branch(const bf16_t* __restrict__ Kb, const bf16_t* __restrict__ Vtb, unsigned char* lds, int nb, int t, int cur, unsigned selmask, unsigned umall,
;                    const bf16x8 (&qf)[4][2], f32x4 (&O)[4][4], float (&m)[4], float (&l)[4], bool online) {
;   const int tid = my_tid(), lane = tid & 63, qi = lane & 15, quad = lane >> 4;
;   const int* blist = (const int*)(lds + NSA_BLIST);
;   const bool isv = tid >= 256;
;   const int t2 = tid & 255;
;   const bf16_t* gsrc = isv ? Vtb + (t2 >> 2) * 32 + (t2 & 3) * 8 : Kb + (long)(t2 >> 3) * 64 + (t2 & 7) * 8;
;   const long gmul = 64;
;   const int ldst = isv ? 32 * NSA_KROW + (t2 >> 2) * NSA_VROW + (t2 & 3) * 16 : (t2 >> 3) * NSA_KROW + (t2 & 7) * 16;
;   unsigned char* slot0 = lds + NSA_SLOT0; unsigned char* slot1 = slot0 + NSA_SLOT;
;   const int N = 2 * nb;
;   auto kbof = [&](int n) { return blist[n >> 1] * 64 + (n & 1) * 32; };
;   u32x4 ra = *(const u32x4*)(gsrc + (long)kbof(0) * gmul), rb = *(const u32x4*)(gsrc + (long)kbof(1) * gmul);
;   *(u32x4*)(slot0 + ldst) = ra;
;   __syncthreads();
; DI void nsa_wave(const Params& p, int layer, int b, int g, int t0, unsigned char* lds, bf16_t* ybase) {
;     ...
;   f32x4 O[4][4]; float m[4], l[4];
; #pragma unroll
;   for (int hh = 0; hh < 4; ++hh) { m[hh] = on_s ? -1e30f : mf_s; l[hh] = 0.f;
; #pragma unroll
;     for (int dt = 0; dt < 4; ++dt) O[hh][dt] = (f32x4){0.f, 0.f, 0.f, 0.f}; }
;   __syncthreads();
;   int nb;
;   {
;     unsigned ub = 0;
; #pragma unroll
;     for (int i = 0; i < 8; ++i) ub |= umw[i];
;     nb = __builtin_popcount(ub);
;     if (my_tid() < 32) { if ((ub >> my_tid()) & 1u) blist[__builtin_popcount(ub & ((1u << my_tid()) - 1u))] = my_tid(); }
;     __syncthreads();
;     nsa_branch<0>(p.ks() + (long)bg * SEQ * 64, p.vst() + (long)bg * 64 * SEQ, lds, nb, t, cur, selmask, umall, qf, O, m, l, on_s);
.LBB0_719:
	s_or_b64 exec, exec, s[0:1]
	v_mov_b32_e32 v2, v210
	s_movk_i32 s0, 0xff
	s_waitcnt lgkmcnt(0)
	s_barrier
	s_nop 0
	v_cmp_lt_i32_e32 vcc, s0, v2
	s_movk_i32 s0, 0x100
	v_cmp_gt_i32_e64 s[0:1], s0, v2
	v_lshlrev_b32_e32 v44, 4, v2
	s_and_saveexec_b64 s[10:11], s[0:1]
	s_xor_b64 s[0:1], exec, s[10:11]
	s_mov_b32 s95, s4
	v_mov_b32_e32 v0, 3
	v_lshrrev_b32_sdwa v0, v0, v2 dst_sel:DWORD dst_unused:UNUSED_PAD src0_sel:DWORD src1_sel:BYTE_0
	v_and_b32_e32 v3, 0x70, v44
	s_movk_i32 s4, 0x90
	v_mad_u32_u24 v3, v0, s4, v3
	s_andn2_saveexec_b64 s[0:1], s[0:1]
	v_mov_b32_e32 v0, 2
	v_lshrrev_b32_sdwa v0, v0, v2 dst_sel:DWORD dst_unused:UNUSED_PAD src0_sel:DWORD src1_sel:BYTE_0
	v_mul_u32_u24_e32 v0, 0x50, v0
	v_and_b32_e32 v3, 48, v44
	s_movk_i32 s4, 0x1200
	v_add3_u32 v3, v0, v3, s4
	s_or_b64 exec, exec, s[0:1]
	s_add_i32 s30, 32, 0x14c00
	v_mov_b32_e32 v49, s30
	ds_read_b32 v49, v49
	v_cndmask_b32_e32 v0, v215, v234, vcc
	v_cndmask_b32_e32 v45, v235, v236, vcc
	v_lshl_add_u64 v[46:47], s[40:41], 0, v[0:1]
	s_lshl_b32 s36, s26, 18
	s_waitcnt lgkmcnt(0)
	v_readfirstlane_b32 s0, v49
	s_lshl_b32 s0, s0, 6
	v_lshlrev_b32_sdwa v0, v238, v2 dst_sel:DWORD dst_unused:UNUSED_PAD src0_sel:DWORD src1_sel:BYTE_0
	s_ashr_i32 s1, s0, 31
	v_lshl_add_u64 v[46:47], v[46:47], 0, s[36:37]
	v_cndmask_b32_e64 v48, v237, 48, vcc
	v_and_b32_e32 v0, v0, v45
	s_lshl_b64 s[10:11], s[0:1], 7
	s_or_b32 s0, s0, 32
	v_lshl_add_u64 v[46:47], v[46:47], 0, v[0:1]
	v_and_b32_e32 v0, v44, v48
	s_ashr_i32 s1, s0, 31
	v_lshl_add_u64 v[168:169], v[46:47], 0, v[0:1]
	s_lshl_b64 s[0:1], s[0:1], 7
	v_lshl_add_u64 v[44:45], v[168:169], 0, s[10:11]
	v_lshl_add_u64 v[48:49], v[168:169], 0, s[0:1]
	global_load_dwordx4 v[44:47], v[44:45], off
	v_add_u32_e32 v161, 32, v3
	global_load_dwordx4 v[108:111], v[48:49], off
	v_add_u32_e32 v172, 0x10000, v161
	s_cmp_eq_u32 s8, 0
	s_waitcnt vmcnt(1)
	ds_write_b128 v172, v[44:47]
	s_waitcnt lgkmcnt(0)
	s_barrier
	s_cbranch_scc1 .LBB0_746
	s_bcnt1_i32_b32 s0, s8
	v_and_b32_e32 v0, 15, v2
	v_bfe_u32 v3, v2, 4, 2
	v_lshlrev_b32_e32 v44, 1, v2
	v_and_b32_e32 v2, 3, v2
	s_lshl_b32 s36, s0, 1
	v_and_or_b32 v2, v44, 24, v2
	v_lshlrev_b32_e32 v44, 4, v3
	v_readlane_b32 s0, v254, 59
	v_cmp_lt_f32_e64 s[8:9], s25, v155
	v_add_u32_e32 v45, s35, v44
	v_add_u32_e32 v47, s0, v44
	v_readlane_b32 s0, v254, 60
	v_mul_u32_u24_e32 v46, 0x90, v2
	v_mul_u32_u24_e32 v48, 0x50, v0
	v_add_u32_e32 v49, s0, v44
	v_readlane_b32 s0, v254, 61
	v_lshlrev_b32_e32 v173, 3, v3
	v_mov_b32_e32 v2, v1
	v_add_u32_e32 v44, s0, v44
	v_mov_b32_e32 v3, v1
	v_cndmask_b32_e64 v180, v155, v232, s[8:9]
	v_mov_b32_e32 v0, v1
	v_mov_b32_e32 v164, 0
	v_add_u32_e32 v176, v45, v46
	v_add_u32_e32 v177, v47, v48
	v_add_u32_e32 v178, v49, v46
	v_add_u32_e32 v179, v44, v48
	v_mov_b64_e32 v[46:47], v[2:3]
	v_mov_b64_e32 v[50:51], v[2:3]
	v_mov_b64_e32 v[54:55], v[2:3]
	v_mov_b64_e32 v[58:59], v[2:3]
	v_mov_b64_e32 v[62:63], v[2:3]
	v_mov_b64_e32 v[66:67], v[2:3]
	v_mov_b64_e32 v[70:71], v[2:3]
	v_mov_b64_e32 v[74:75], v[2:3]
	v_mov_b64_e32 v[78:79], v[2:3]
	v_mov_b64_e32 v[82:83], v[2:3]
	v_mov_b64_e32 v[86:87], v[2:3]
	v_mov_b64_e32 v[90:91], v[2:3]
	v_mov_b64_e32 v[94:95], v[2:3]
	v_mov_b64_e32 v[98:99], v[2:3]
	v_mov_b64_e32 v[102:103], v[2:3]
	v_mov_b64_e32 v[106:107], v[2:3]
	s_add_i32 s43, s36, -2
	s_mov_b32 s54, 3
	s_add_i32 s55, s36, -1
	v_or_b32_e32 v174, 32, v173
	s_add_i32 s56, 32, 0x14c00
	v_lshlrev_b32_e32 v217, 2, v228
	v_add_u32_e32 v217, 0x14c20, v217
	ds_read_b32 v216, v217
	s_waitcnt lgkmcnt(0)
	v_mov_b64_e32 v[44:45], v[0:1]
	v_mov_b64_e32 v[48:49], v[0:1]
	v_mov_b64_e32 v[52:53], v[0:1]
	v_mov_b64_e32 v[56:57], v[0:1]
	v_mov_b64_e32 v[60:61], v[0:1]
	v_mov_b64_e32 v[64:65], v[0:1]
	v_mov_b64_e32 v[68:69], v[0:1]
	v_mov_b64_e32 v[72:73], v[0:1]
	v_mov_b64_e32 v[76:77], v[0:1]
	v_mov_b64_e32 v[80:81], v[0:1]
	v_mov_b64_e32 v[84:85], v[0:1]
	v_mov_b64_e32 v[88:89], v[0:1]
	v_mov_b64_e32 v[92:93], v[0:1]
	v_mov_b64_e32 v[96:97], v[0:1]
	v_mov_b64_e32 v[100:101], v[0:1]
	v_mov_b64_e32 v[104:105], v[0:1]
	v_mov_b32_e32 v0, v180
	v_mov_b32_e32 v2, v180
	v_mov_b32_e32 v3, v180
	v_mov_b32_e32 v165, v164
	v_mov_b32_e32 v166, v164
	v_mov_b32_e32 v167, v164
	s_branch .LBB0_727

; #define MFMA16(a, b, c) __builtin_amdgcn_mfma_f32_16x16x32_bf16((a), (b), (c), 0, 0, 0)
; template <int MODE>
; DI void nsa_chunk(const KVFrag& f, int kb, int t, bool selbit, const bf16x8 (&qf)[4][2], f32x4 (&O)[4][4], float (&m)[4], float (&l)[4], int quad, bool online) {
;   const float SC = 0.125f * 1.44269504089f;
;   bool val[8];
; #pragma unroll
;   for (int idx = 0; idx < 8; ++idx) {
;     const int key = kb + 8 * quad + idx;
;     val[idx] = MODE == 0 ? (selbit && key <= t) : (key <= t && key > t - 512);
;   }
; #pragma unroll
;   for (int hh = 0; hh < 4; ++hh) {
;     f32x4 s[2];
; #pragma unroll
;     for (int a = 0; a < 2; ++a) { s[a] = MFMA16(f.k[a][0], qf[hh][0], ((f32x4){0.f, 0.f, 0.f, 0.f})); s[a] = MFMA16(f.k[a][1], qf[hh][1], s[a]); }
;     float mn = m[hh];
;     if (online) {
;       float cm = -1e30f;
; #pragma unroll
;       for (int idx = 0; idx < 8; ++idx) if (val[idx]) cm = fmaxf(cm, s[idx >> 2][idx & 3] * SC);
;       cm = fmaxf(cm, __shfl_xor(cm, 16)); cm = fmaxf(cm, __shfl_xor(cm, 32));
;       mn = fmaxf(mn, cm);
;       const float alpha = __builtin_amdgcn_exp2f(m[hh] - mn);
;       m[hh] = mn; l[hh] *= alpha;
; #pragma unroll
;       for (int dt = 0; dt < 4; ++dt) O[hh][dt] = O[hh][dt] * alpha;
;     }
; template <int MODE>
; DI void nsa_branch(const bf16_t* __restrict__ Kb, const bf16_t* __restrict__ Vtb, unsigned char* lds, int nb, int t, int cur, unsigned selmask, unsigned umall,
;                    const bf16x8 (&qf)[4][2], f32x4 (&O)[4][4], float (&m)[4], float (&l)[4], bool online) {
;     ...
;   for (int n = 0; n < N; n += 2) {
;     const int j = blist[n >> 1];
;     const bool won = MODE == 0 ? ((umall >> j) & 1u) != 0 : (j >= cur - 8 && j <= cur);
;     const bool bit = (selmask >> j) & 1u;
;     ra = *(const u32x4*)(gsrc + (long)kbof(min(n + 2, N - 2)) * gmul);
;     if (won) { KVFrag f; nsa_ldsfrag(f, slot0, qi, quad); nsa_chunk<MODE>(f, j * 64, t, bit, qf, O, m, l, quad, online); }
.LBB0_727:
	s_sub_u32 s58, s56, 0x14c20
	s_lshr_b32 s58, s58, 2
	v_readlane_b32 s0, v216, s58
	s_nop 1
	v_mov_b32_e32 v181, s0
	s_lshl_b32 s10, 1, s0
	s_and_b32 s11, s10, s42
	s_cmp_lg_u32 s11, 0
	s_cselect_b64 s[0:1], -1, 0
	s_add_i32 s57, s54, -1
	s_min_i32 s12, s57, s43
	s_lshr_b32 s12, s12, 1
	v_readlane_b32 s58, v216, s12
	v_and_b32_e32 v116, s10, v171
	v_cmp_ne_u32_e64 s[12:13], 0, v116
	v_cndmask_b32_e64 v116, 0, 1, s[8:9]
	s_lshl_b32 s58, s58, 6
	s_ashr_i32 s59, s58, 31
	s_lshl_b64 s[58:59], s[58:59], 7
	s_cmp_eq_u32 s11, 0
	v_lshl_add_u64 v[112:113], v[168:169], 0, s[58:59]
	global_load_dwordx4 v[112:115], v[112:113], off
	v_cmp_ne_u32_e64 s[10:11], 1, v116
	s_cbranch_scc1 .LBB0_737
	v_lshl_or_b32 v182, v181, 6, v173
	v_cmp_le_i32_e32 vcc, v182, v160
	s_and_b64 s[16:17], s[12:13], vcc
	v_cmp_lt_i32_e32 vcc, v182, v160
	v_or_b32_e32 v148, 2, v182
	s_and_b64 s[18:19], s[12:13], vcc
	v_cmp_le_i32_e32 vcc, v148, v160
	v_or_b32_e32 v148, 3, v182
	s_and_b64 s[44:45], s[12:13], vcc
	v_cmp_le_i32_e32 vcc, v148, v160
	v_or_b32_e32 v148, 4, v182
	ds_read_b128 v[136:139], v176
	ds_read_b128 v[140:143], v176 offset:64
	ds_read_b128 v[144:147], v176 offset:576
	ds_read_b128 v[132:135], v176 offset:640
	ds_read_b128 v[128:131], v177
	ds_read_b128 v[124:127], v177 offset:1280
	ds_read_b128 v[120:123], v177 offset:2560
	ds_read_b128 v[116:119], v177 offset:3840
	s_and_b64 s[46:47], s[12:13], vcc
	v_cmp_le_i32_e32 vcc, v148, v160
	s_waitcnt lgkmcnt(7)
	v_mfma_f32_16x16x32_bf16 v[148:151], v[136:139], v[8:11], 0
	v_or_b32_e32 v152, 5, v182
	s_and_b64 s[14:15], s[12:13], vcc
	v_cmp_le_i32_e32 vcc, v152, v160
	s_waitcnt lgkmcnt(6)
	v_mfma_f32_16x16x32_bf16 v[152:155], v[140:143], v[12:15], v[148:151]
	v_or_b32_e32 v183, 6, v182
	s_and_b64 s[48:49], s[12:13], vcc
	v_cmp_le_i32_e32 vcc, v183, v160
	s_waitcnt lgkmcnt(5)
	v_mfma_f32_16x16x32_bf16 v[148:151], v[144:147], v[8:11], 0
	v_or_b32_e32 v182, 7, v182
	s_and_b64 s[50:51], s[12:13], vcc
	v_cmp_le_i32_e32 vcc, v182, v160
	s_waitcnt lgkmcnt(4)
	v_mfma_f32_16x16x32_bf16 v[148:151], v[132:135], v[12:15], v[148:151]
	s_and_b64 s[52:53], s[12:13], vcc
	s_and_b64 vcc, exec, s[10:11]
	s_cbranch_vccnz .LBB0_730
	v_mul_f32_e32 v182, 0x3e38aa3b, v152
	v_max_f32_e32 v182, 0xf149f2ca, v182
	v_cndmask_b32_e64 v182, v232, v182, s[16:17]
	v_mul_f32_e32 v183, 0x3e38aa3b, v153
	v_max_f32_e32 v183, v182, v183
	v_cndmask_b32_e64 v182, v182, v183, s[18:19]
	v_mul_f32_e32 v183, 0x3e38aa3b, v154
	v_max_f32_e32 v183, v182, v183
	v_cndmask_b32_e64 v182, v182, v183, s[44:45]
	v_mul_f32_e32 v183, 0x3e38aa3b, v155
	v_max_f32_e32 v183, v182, v183
	v_cndmask_b32_e64 v182, v182, v183, s[46:47]
	v_mul_f32_e32 v183, 0x3e38aa3b, v148
	v_max_f32_e32 v183, v182, v183
	v_cndmask_b32_e64 v182, v182, v183, s[14:15]
	v_mul_f32_e32 v183, 0x3e38aa3b, v149
	v_max_f32_e32 v184, v182, v182
	v_max_f32_e32 v183, v184, v183
	v_cndmask_b32_e64 v182, v182, v183, s[48:49]
	v_mul_f32_e32 v183, 0x3e38aa3b, v150
	v_max_f32_e32 v184, v182, v182
	v_max_f32_e32 v183, v184, v183
	v_cndmask_b32_e64 v182, v182, v183, s[50:51]
	v_mul_f32_e32 v183, 0x3e38aa3b, v151
	v_max_f32_e32 v184, v182, v182
	v_max_f32_e32 v183, v184, v183
	v_cndmask_b32_e64 v182, v182, v183, s[52:53]
	ds_bpermute_b32 v183, v175, v182
	v_max_f32_e32 v182, v182, v182
	s_waitcnt lgkmcnt(0)
	v_max_f32_e32 v183, v183, v183
	v_max_f32_e32 v182, v182, v183
	ds_bpermute_b32 v183, v159, v182
	s_waitcnt lgkmcnt(0)
	v_max3_f32 v183, v3, v182, v183
	v_sub_f32_e32 v3, v3, v183
	v_exp_f32_e32 v182, v3
	v_mov_b32_e32 v3, v183
	v_mul_f32_e32 v167, v167, v182
	v_pk_mul_f32 v[106:107], v[106:107], v[182:183] op_sel_hi:[1,0]
	v_pk_mul_f32 v[104:105], v[104:105], v[182:183] op_sel_hi:[1,0]
	v_pk_mul_f32 v[102:103], v[102:103], v[182:183] op_sel_hi:[1,0]
	v_pk_mul_f32 v[100:101], v[100:101], v[182:183] op_sel_hi:[1,0]
	v_pk_mul_f32 v[98:99], v[98:99], v[182:183] op_sel_hi:[1,0]
	v_pk_mul_f32 v[96:97], v[96:97], v[182:183] op_sel_hi:[1,0]
	v_pk_mul_f32 v[94:95], v[94:95], v[182:183] op_sel_hi:[1,0]
	v_pk_mul_f32 v[92:93], v[92:93], v[182:183] op_sel_hi:[1,0]

; #define MFMA16(a, b, c) __builtin_amdgcn_mfma_f32_16x16x32_bf16((a), (b), (c), 0, 0, 0)
; template <int MODE>
; DI void nsa_chunk(const KVFrag& f, int kb, int t, bool selbit, const bf16x8 (&qf)[4][2], f32x4 (&O)[4][4], float (&m)[4], float (&l)[4], int quad, bool online) {
;   const float SC = 0.125f * 1.44269504089f;
;   bool val[8];
; #pragma unroll
;   for (int idx = 0; idx < 8; ++idx) {
;     const int key = kb + 8 * quad + idx;
;     val[idx] = MODE == 0 ? (selbit && key <= t) : (key <= t && key > t - 512);
;   }
; #pragma unroll
;   for (int hh = 0; hh < 4; ++hh) {
;     f32x4 s[2];
; #pragma unroll
;     for (int a = 0; a < 2; ++a) { s[a] = MFMA16(f.k[a][0], qf[hh][0], ((f32x4){0.f, 0.f, 0.f, 0.f})); s[a] = MFMA16(f.k[a][1], qf[hh][1], s[a]); }
;     float mn = m[hh];
;     if (online) {
;       float cm = -1e30f;
; #pragma unroll
;       for (int idx = 0; idx < 8; ++idx) if (val[idx]) cm = fmaxf(cm, s[idx >> 2][idx & 3] * SC);
;       cm = fmaxf(cm, __shfl_xor(cm, 16)); cm = fmaxf(cm, __shfl_xor(cm, 32));
;       mn = fmaxf(mn, cm);
;       const float alpha = __builtin_amdgcn_exp2f(m[hh] - mn);
;       m[hh] = mn; l[hh] *= alpha;
; #pragma unroll
;       for (int dt = 0; dt < 4; ++dt) O[hh][dt] = O[hh][dt] * alpha;
;     }
; template <int MODE>
; DI void nsa_branch(const bf16_t* __restrict__ Kb, const bf16_t* __restrict__ Vtb, unsigned char* lds, int nb, int t, int cur, unsigned selmask, unsigned umall,
;                    const bf16x8 (&qf)[4][2], f32x4 (&O)[4][4], float (&m)[4], float (&l)[4], bool online) {
;     ...
;     *(u32x4*)(slot1 + ldst) = rb;
;     __syncthreads();
;     rb = *(const u32x4*)(gsrc + (long)kbof(min(n + 3, N - 1)) * gmul);
;     if (won) { KVFrag f; nsa_ldsfrag(f, slot1, qi, quad); nsa_chunk<MODE>(f, j * 64 + 32, t, bit, qf, O, m, l, quad, online); }
.LBB0_737:
	s_min_i32 s14, s54, s55
	s_lshr_b32 s14, s14, 1
	v_add_u32_e32 v116, 0x12600, v161
	s_waitcnt vmcnt(1)
	ds_write_b128 v116, v[108:111]
	s_waitcnt lgkmcnt(0)
	s_barrier
	v_readlane_b32 s14, v216, s14
	s_andn2_b64 vcc, exec, s[0:1]
	s_lshl_b32 s14, s14, 6
	s_or_b32 s14, s14, 32
	s_ashr_i32 s15, s14, 31
	s_lshl_b64 s[14:15], s[14:15], 7
	v_lshl_add_u64 v[108:109], v[168:169], 0, s[14:15]
	global_load_dwordx4 v[108:111], v[108:109], off
	s_cbranch_vccnz .LBB0_726
	v_lshl_or_b32 v181, v181, 6, v174
	v_cmp_le_i32_e32 vcc, v181, v160
	s_and_b64 s[16:17], s[12:13], vcc
	v_cmp_lt_i32_e32 vcc, v181, v160
	v_or_b32_e32 v148, 2, v181
	s_and_b64 s[18:19], s[12:13], vcc
	v_cmp_le_i32_e32 vcc, v148, v160
	v_or_b32_e32 v148, 3, v181
	s_and_b64 s[44:45], s[12:13], vcc
	v_cmp_le_i32_e32 vcc, v148, v160
	v_or_b32_e32 v148, 4, v181
	ds_read_b128 v[136:139], v178
	ds_read_b128 v[140:143], v178 offset:64
	ds_read_b128 v[144:147], v178 offset:576
	ds_read_b128 v[132:135], v178 offset:640
	ds_read_b128 v[128:131], v179
	ds_read_b128 v[124:127], v179 offset:1280
	ds_read_b128 v[120:123], v179 offset:2560
	ds_read_b128 v[116:119], v179 offset:3840
	s_and_b64 s[46:47], s[12:13], vcc
	v_cmp_le_i32_e32 vcc, v148, v160
	s_waitcnt lgkmcnt(7)
	v_mfma_f32_16x16x32_bf16 v[148:151], v[136:139], v[8:11], 0
	v_or_b32_e32 v152, 5, v181
	s_and_b64 s[14:15], s[12:13], vcc
	v_cmp_le_i32_e32 vcc, v152, v160
	s_waitcnt lgkmcnt(6)
	v_mfma_f32_16x16x32_bf16 v[152:155], v[140:143], v[12:15], v[148:151]
	v_or_b32_e32 v182, 6, v181
	s_and_b64 s[48:49], s[12:13], vcc
	v_cmp_le_i32_e32 vcc, v182, v160
	s_waitcnt lgkmcnt(5)
	v_mfma_f32_16x16x32_bf16 v[148:151], v[144:147], v[8:11], 0
	v_or_b32_e32 v181, 7, v181
	s_and_b64 s[50:51], s[12:13], vcc
	v_cmp_le_i32_e32 vcc, v181, v160
	s_waitcnt lgkmcnt(4)
	v_mfma_f32_16x16x32_bf16 v[148:151], v[132:135], v[12:15], v[148:151]
	s_and_b64 s[12:13], s[12:13], vcc
	s_and_b64 vcc, exec, s[10:11]
	s_cbranch_vccnz .LBB0_740
	v_mul_f32_e32 v181, 0x3e38aa3b, v152
	v_max_f32_e32 v181, 0xf149f2ca, v181
	v_cndmask_b32_e64 v181, v232, v181, s[16:17]
	v_mul_f32_e32 v182, 0x3e38aa3b, v153
	v_max_f32_e32 v182, v181, v182
	v_cndmask_b32_e64 v181, v181, v182, s[18:19]
	v_mul_f32_e32 v182, 0x3e38aa3b, v154
	v_max_f32_e32 v182, v181, v182
	v_cndmask_b32_e64 v181, v181, v182, s[44:45]
	v_mul_f32_e32 v182, 0x3e38aa3b, v155
	v_max_f32_e32 v182, v181, v182
	v_cndmask_b32_e64 v181, v181, v182, s[46:47]
	v_mul_f32_e32 v182, 0x3e38aa3b, v148
	v_max_f32_e32 v182, v181, v182
	v_cndmask_b32_e64 v181, v181, v182, s[14:15]
	v_mul_f32_e32 v182, 0x3e38aa3b, v149
	v_max_f32_e32 v183, v181, v181
	v_max_f32_e32 v182, v183, v182
	v_cndmask_b32_e64 v181, v181, v182, s[48:49]
	v_mul_f32_e32 v182, 0x3e38aa3b, v150
	v_max_f32_e32 v183, v181, v181
	v_max_f32_e32 v182, v183, v182
	v_cndmask_b32_e64 v181, v181, v182, s[50:51]
	v_mul_f32_e32 v182, 0x3e38aa3b, v151
	v_max_f32_e32 v183, v181, v181
	v_max_f32_e32 v182, v183, v182
	v_cndmask_b32_e64 v181, v181, v182, s[12:13]
	ds_bpermute_b32 v182, v175, v181
	v_max_f32_e32 v181, v181, v181
	s_waitcnt lgkmcnt(0)
	v_max_f32_e32 v182, v182, v182
	v_max_f32_e32 v181, v181, v182
	ds_bpermute_b32 v182, v159, v181
	s_waitcnt lgkmcnt(0)
	v_max3_f32 v181, v3, v181, v182
	v_sub_f32_e32 v3, v3, v181
	v_exp_f32_e32 v182, v3
	v_mov_b32_e32 v3, v181
	v_mul_f32_e32 v167, v167, v182
	v_pk_mul_f32 v[106:107], v[106:107], v[182:183] op_sel_hi:[1,0]
	v_pk_mul_f32 v[104:105], v[104:105], v[182:183] op_sel_hi:[1,0]
	v_pk_mul_f32 v[102:103], v[102:103], v[182:183] op_sel_hi:[1,0]
	v_pk_mul_f32 v[100:101], v[100:101], v[182:183] op_sel_hi:[1,0]
	v_pk_mul_f32 v[98:99], v[98:99], v[182:183] op_sel_hi:[1,0]
	v_pk_mul_f32 v[96:97], v[96:97], v[182:183] op_sel_hi:[1,0]
	v_pk_mul_f32 v[94:95], v[94:95], v[182:183] op_sel_hi:[1,0]
	v_pk_mul_f32 v[92:93], v[92:93], v[182:183] op_sel_hi:[1,0]
